# static s_setprio 1 for waves 0-3 through each GEMM phase (other half at 0), per-block priority flips deleted
# speedup vs baseline: 1.0080x; 1.0001x over previous
; #define PG8_BAR __builtin_amdgcn_s_barrier()
;     __host__ __device__ bool next(int i, Unit& u) const {
;         long L = (long)i * G + c;
;         if (pack_last && dup == 1 && i == nwg / G && (nwg % G)) { const int x = c & 7, k = c >> 3; if (x >= 4) return false; L = (long)i * G + (k & 15) * 8 + (k < 16 ? x : x + 4); }
;         if (L >= (long)nwg * dup) return false; if (L >= nwg) L -= nwg;
;         int wgid = (int)L; { const int q = nwg / NXCD, r = nwg % NXCD, xcd = wgid % NXCD, off = wgid / NXCD; wgid = (xcd < r ? xcd * (q + 1) : r * (q + 1) + (xcd - r) * q) + off; }
;         const int nig = WGM * nN, gid = wgid / nig, fm = gid * WGM, gsz = (nM - fm) < WGM ? (nM - fm) : WGM;
;         u.pm = fm + ((wgid % nig) % gsz); u.pn = (wgid % nig) / gsz; u.kt0 = 0; u.ntu = ntk; return true;
; template <class Epi, class Sched, bool ALIGN_EPI = false, bool SP2 = false>
; __device__ __forceinline__ void gemm_phase(PG8_LAS unsigned char* lds, const Gemm g, const Sched& S, const Epi& E) {
;     ...
;     for (int i = 0; i < 2; ++i) { int R, C; stage_rc(tid * 16 + i * 8192, R, C); const int Rb = Epi::PERM ? ((R & ~31) + perm32(R & 31)) : R;
;         voffA[i] = (unsigned)(R * K + C) * 2u; voffB[i] = (unsigned)(Rb * K + C) * 2u; }
;     const size_t kstep = (size_t)(BK * 2);
;     const size_t hstep = (size_t)HALF * K * 2;
;     const size_t tstep = 2 * hstep;
;     const unsigned ldsw = (unsigned)wid * 1024u;
;     const int aoff = lds_byte(wr * 64 + fr, fq * 8), boff = lds_byte(wc * 32 + fr, fq * 8);
;     ...
;     Unit cur, nxt; int ui = 0;
;     if (!S.next(0, cur)) return;
;     f32x4 acc[2][2][4][2];
; #pragma unroll
;     for (int a = 0; a < 2; ++a)
; #pragma unroll
;         for (int b = 0; b < 2; ++b)
; #pragma unroll
;             for (int m = 0; m < 4; ++m)
; #pragma unroll
;                 for (int n = 0; n < 2; ++n) acc[a][b][m][n] = (f32x4){0.f, 0.f, 0.f, 0.f};
;     bf16x8 At[4][2], B0[2][2], B1[2][2];
;     const char* cA = (const char*)g.A + (size_t)cur.pm * tstep + (size_t)cur.kt0 * kstep; const char* cB = (const char*)g.Bt + (size_t)cur.pn * tstep + (size_t)cur.kt0 * kstep;
;     S.a_ready(cur);
;     if constexpr (SP2) {
;         PG8_STAGE(PG8_SB(0, 0), cB, voffB); PG8_STAGE(PG8_SB(0, 1), cB + hstep, voffB); PG8_STAGE(PG8_SA(0, 0), cA, voffA); PG8_STAGE(PG8_SA(0, 1), cA + hstep, voffA);
;         if (wr == 1) PG8_BAR;
.LBB0_353:
	s_cmpk_lg_i32 s33, 0x100
	s_cselect_b64 s[16:17], -1, 0
	s_cmpk_eq_i32 s33, 0x100
	s_cselect_b64 s[54:55], -1, 0
	s_ashr_i32 s1, s33, 31
	s_and_b32 s5, s2, 7
	s_ashr_i32 s3, s2, 31
	v_writelane_b32 v255, s1, 10
	s_and_b32 s1, s2, 0x78
	s_or_b32 s4, s5, 4
	s_cmpk_lt_i32 s2, 0x80
	s_cselect_b32 s4, s5, s4
	s_or_b32 s1, s1, s4
	v_writelane_b32 v255, s5, 11
	s_andn2_b64 vcc, exec, s[6:7]
	s_or_b32 s51, s1, 0x700
	s_cbranch_vccnz .LBB0_608
	v_ashrrev_i32_e32 v2, 31, v11
	v_lshrrev_b32_e32 v2, 26, v2
	v_add_u32_e32 v2, v11, v2
	v_ashrrev_i32_e32 v10, 6, v2
	v_bfe_i32 v2, v11, 27, 1
	v_lshlrev_b32_e32 v1, 4, v11
	v_lshrrev_b32_e32 v2, 22, v2
	v_add_u32_e32 v2, v1, v2
	v_and_b32_e32 v2, 0xfffffc00, v2
	v_sub_u32_e32 v2, v1, v2
	v_lshrrev_b32_e32 v3, 4, v2
	v_bitop3_b32 v2, v3, v2, 32 bitop3:0x6c
	v_ashrrev_i32_e32 v4, 31, v2
	v_lshrrev_b32_e32 v4, 26, v4
	v_add_u32_e32 v4, v2, v4
	v_lshlrev_b32_e32 v3, 3, v10
	v_ashrrev_i32_e32 v12, 6, v4
	v_and_b32_e32 v4, 0xc0, v4
	v_and_b32_e32 v3, -16, v3
	v_sub_u32_e32 v2, v2, v4
	v_mov_b32_e32 v4, 1
	v_add_u32_e32 v3, v12, v3
	v_ashrrev_i16_sdwa v2, v4, sext(v2) dst_sel:DWORD dst_unused:UNUSED_PAD src0_sel:DWORD src1_sel:BYTE_0
	v_lshlrev_b32_e32 v5, 5, v10
	v_bfe_i32 v13, v2, 0, 16
	v_lshlrev_b32_e32 v2, 1, v3
	v_lshrrev_b32_e32 v6, 2, v3
	v_and_b32_e32 v7, 3, v12
	s_mov_b32 s4, 0x7ffe0
	v_and_b32_e32 v5, 32, v5
	v_and_b32_e32 v2, 24, v2
	v_and_b32_e32 v6, 4, v6
	v_and_or_b32 v7, v3, s4, v7
	v_or3_b32 v2, v7, v6, v2
	v_add_lshl_u32 v5, v5, v13, 1
	v_add_u32_e32 v1, 0x2000, v1
	v_lshl_add_u32 v144, v2, 13, v5
	v_ashrrev_i32_e32 v2, 31, v1
	v_lshrrev_b32_e32 v2, 22, v2
	v_add_u32_e32 v2, v1, v2
	v_ashrrev_i32_e32 v14, 10, v2
	v_mul_i32_i24_e32 v2, 0x400, v14
	v_sub_u32_e32 v1, v1, v2
	v_lshrrev_b32_e32 v2, 4, v1
	v_bitop3_b32 v1, v2, v1, 32 bitop3:0x6c
	v_lshl_add_u32 v142, v3, 13, v5
	v_ashrrev_i32_e32 v3, 31, v1
	v_lshrrev_b32_e32 v3, 26, v3
	v_writelane_b32 v255, s54, 12
	s_waitcnt lgkmcnt(0)
	s_add_u32 s53, s26, 0x14100000
	v_add_u32_e32 v3, v1, v3
	v_writelane_b32 v255, s55, 13
	s_addc_u32 s55, s27, 0
	v_lshlrev_b32_e32 v2, 3, v14
	v_ashrrev_i32_e32 v15, 6, v3
	v_and_b32_e32 v3, 0xc0, v3
	s_add_u32 s57, s26, 0x45900000
	v_and_b32_e32 v2, -16, v2
	v_sub_u32_e32 v1, v1, v3
	s_addc_u32 s65, s27, 0
	s_ashr_i32 s1, s0, 6
	v_add_u32_e32 v2, v15, v2
	v_ashrrev_i16_sdwa v1, v4, sext(v1) dst_sel:DWORD dst_unused:UNUSED_PAD src0_sel:DWORD src1_sel:BYTE_0
	v_and_b32_e32 v4, 3, v15
	s_ashr_i32 s79, s78, 31
	s_ashr_i32 s77, s76, 31
	v_and_or_b32 v4, v2, s4, v4
	s_ashr_i32 s4, s0, 8
	s_lshl_b32 s67, s1, 10
	s_lshl_b64 s[6:7], s[78:79], 21
	s_lshl_b64 s[8:9], s[76:77], 21
	s_add_u32 s12, s57, s8
	v_lshlrev_b32_e32 v5, 5, v14
	v_bfe_i32 v16, v1, 0, 16
	v_lshlrev_b32_e32 v1, 1, v2
	v_lshrrev_b32_e32 v3, 2, v2
	s_addc_u32 s13, s65, s9
	s_add_i32 s79, s67, 0
	v_and_b32_e32 v5, 32, v5
	v_and_b32_e32 v1, 24, v1
	v_and_b32_e32 v3, 4, v3
	s_add_i32 m0, s79, 0x10000
	v_or3_b32 v1, v4, v3, v1
	v_add_lshl_u32 v3, v5, v16, 1
	global_load_lds_dwordx4 v144, s[12:13]
	s_add_i32 m0, s79, 0x12000
	v_lshl_add_u32 v148, v1, 13, v3
	s_add_u32 s8, s12, 0x100000
	global_load_lds_dwordx4 v148, s[12:13]
	s_addc_u32 s9, s13, 0
	s_add_i32 m0, s79, 0x14000
	v_lshl_add_u32 v146, v2, 13, v3
	global_load_lds_dwordx4 v144, s[8:9]
	s_add_i32 m0, s79, 0x16000
	s_add_u32 s10, s53, s6
	s_addc_u32 s11, s55, s7
	s_add_i32 s88, s79, 0x2000
	global_load_lds_dwordx4 v148, s[8:9]
	s_mov_b32 m0, s79
	s_add_u32 s6, s10, 0x100000
	global_load_lds_dwordx4 v142, s[10:11]
	s_mov_b32 m0, s88
	s_addc_u32 s7, s11, 0
	s_add_i32 s89, s79, 0x4000
	global_load_lds_dwordx4 v146, s[10:11]
	s_mov_b32 m0, s89
	s_add_i32 s90, s79, 0x6000
	global_load_lds_dwordx4 v142, s[6:7]
	s_mov_b32 m0, s90
	v_mov_b32_e32 v151, 0
	global_load_lds_dwordx4 v146, s[6:7]
	v_mov_b32_e32 v145, v151
	v_mov_b32_e32 v149, v151
	v_mov_b32_e32 v143, v151
	v_mov_b32_e32 v147, v151
	s_cmp_eq_u32 s4, 1
	s_mov_b64 s[58:59], s[96:97]
	s_mov_b32 s91, 0
	v_lshl_add_u64 v[8:9], s[12:13], 0, v[144:145]
	v_lshl_add_u64 v[6:7], s[12:13], 0, v[148:149]
	v_lshl_add_u64 v[2:3], s[10:11], 0, v[142:143]
	s_cselect_b64 s[18:19], -1, 0
	s_cmp_lg_u32 s4, 1
	v_lshl_add_u64 v[4:5], s[10:11], 0, v[146:147]
	s_setprio 1
	s_cbranch_scc1 .LBB0_356
	s_barrier
	s_setprio 0

; #define PG8_STAGE(bufoff, gbase, voff) do { _Pragma("unroll") for (int _i = 0; _i < 2; ++_i) \
;         __builtin_amdgcn_global_load_lds((const unsigned*)((const char*)(gbase) + (voff)[_i]), (PG8_LAS unsigned*)(lds + (bufoff) + ldsw + _i * 8192), 16, 0, 0); } while (0)
; #define PG8_BAR __builtin_amdgcn_s_barrier()
; template <class Epi, class Sched, bool ALIGN_EPI = false, bool SP2 = false>
; __device__ __forceinline__ void gemm_phase(PG8_LAS unsigned char* lds, const Gemm g, const Sched& S, const Epi& E) {
;     ...
;     for (int i = 0; i < 2; ++i) { int R, C; stage_rc(tid * 16 + i * 8192, R, C); const int Rb = Epi::PERM ? ((R & ~31) + perm32(R & 31)) : R;
;         voffA[i] = (unsigned)(R * K + C) * 2u; voffB[i] = (unsigned)(Rb * K + C) * 2u; }
;     const size_t kstep = (size_t)(BK * 2);
;     const size_t hstep = (size_t)HALF * K * 2;
;     const size_t tstep = 2 * hstep;
;     const unsigned ldsw = (unsigned)wid * 1024u;
;     const int aoff = lds_byte(wr * 64 + fr, fq * 8), boff = lds_byte(wc * 32 + fr, fq * 8);
;     ...
;     Unit cur, nxt; int ui = 0;
;     if (!S.next(0, cur)) return;
;     f32x4 acc[2][2][4][2];
; #pragma unroll
;     for (int a = 0; a < 2; ++a)
; #pragma unroll
;         for (int b = 0; b < 2; ++b)
; #pragma unroll
;             for (int m = 0; m < 4; ++m)
; #pragma unroll
;                 for (int n = 0; n < 2; ++n) acc[a][b][m][n] = (f32x4){0.f, 0.f, 0.f, 0.f};
;     bf16x8 At[4][2], B0[2][2], B1[2][2];
;     const char* cA = (const char*)g.A + (size_t)cur.pm * tstep + (size_t)cur.kt0 * kstep; const char* cB = (const char*)g.Bt + (size_t)cur.pn * tstep + (size_t)cur.kt0 * kstep;
;     S.a_ready(cur);
;     if constexpr (SP2) {
;         PG8_STAGE(PG8_SB(0, 0), cB, voffB); PG8_STAGE(PG8_SB(0, 1), cB + hstep, voffB); PG8_STAGE(PG8_SA(0, 0), cA, voffA); PG8_STAGE(PG8_SA(0, 1), cA + hstep, voffA);
;         if (wr == 1) PG8_BAR;
.LBB0_2469:
	s_andn2_b64 vcc, exec, s[14:15]
	s_cbranch_vccnz .LBB0_2518
	v_ashrrev_i32_e32 v2, 31, v3
	v_lshrrev_b32_e32 v2, 26, v2
	v_add_u32_e32 v2, v3, v2
	v_ashrrev_i32_e32 v12, 6, v2
	v_bfe_i32 v2, v3, 27, 1
	v_lshlrev_b32_e32 v1, 4, v3
	v_lshrrev_b32_e32 v2, 22, v2
	v_add_u32_e32 v2, v1, v2
	v_and_b32_e32 v2, 0xfffffc00, v2
	v_sub_u32_e32 v2, v1, v2
	v_lshrrev_b32_e32 v4, 4, v2
	v_bitop3_b32 v2, v4, v2, 32 bitop3:0x6c
	v_ashrrev_i32_e32 v5, 31, v2
	v_lshrrev_b32_e32 v5, 26, v5
	v_add_u32_e32 v5, v2, v5
	v_ashrrev_i32_e32 v13, 6, v5
	v_and_b32_e32 v5, 0xc0, v5
	v_sub_u32_e32 v2, v2, v5
	v_mov_b32_e32 v5, 1
	v_lshlrev_b32_e32 v4, 3, v12
	v_lshlrev_b32_e32 v6, 5, v12
	v_ashrrev_i16_sdwa v2, v5, sext(v2) dst_sel:DWORD dst_unused:UNUSED_PAD src0_sel:DWORD src1_sel:BYTE_0
	s_load_dwordx2 s[6:7], s[6:7], 0xe8
	v_and_b32_e32 v4, 0x7fff0, v4
	v_and_b32_e32 v6, 32, v6
	v_bfe_i32 v14, v2, 0, 16
	v_add_u32_e32 v2, v6, v14
	v_add_lshl_u32 v4, v13, v4, 13
	v_add_u32_e32 v1, 0x2000, v1
	v_lshl_add_u32 v134, v2, 1, v4
	v_ashrrev_i32_e32 v2, 31, v1
	v_lshrrev_b32_e32 v2, 22, v2
	v_add_u32_e32 v2, v1, v2
	s_waitcnt lgkmcnt(0)
	s_add_u32 s1, s6, 0x3d500000
	v_ashrrev_i32_e32 v15, 10, v2
	s_addc_u32 s28, s7, 0
	v_mul_i32_i24_e32 v2, 0x400, v15
	s_add_u32 s29, s6, 0x49300000
	v_sub_u32_e32 v1, v1, v2
	s_addc_u32 s54, s7, 0
	s_ashr_i32 s16, s20, 6
	v_lshrrev_b32_e32 v2, 4, v1
	s_ashr_i32 s13, s12, 31
	s_ashr_i32 s9, s8, 31
	s_ashr_i32 s11, s10, 31
	v_bitop3_b32 v1, v2, v1, 32 bitop3:0x6c
	s_ashr_i32 s17, s20, 8
	s_lshl_b32 s55, s16, 10
	s_lshl_b64 s[14:15], s[12:13], 21
	s_lshl_b64 s[18:19], s[8:9], 7
	s_lshl_b64 s[22:23], s[10:11], 21
	v_ashrrev_i32_e32 v4, 31, v1
	s_add_u32 s9, s29, s22
	v_lshrrev_b32_e32 v4, 26, v4
	s_addc_u32 s11, s54, s23
	v_add_u32_e32 v4, v1, v4
	s_add_u32 s46, s9, s18
	v_ashrrev_i32_e32 v16, 6, v4
	v_and_b32_e32 v4, 0xc0, v4
	s_addc_u32 s47, s11, s19
	s_add_i32 s11, s55, 0
	v_sub_u32_e32 v1, v1, v4
	s_add_i32 m0, s11, 0x10000
	v_lshlrev_b32_e32 v2, 3, v15
	v_lshlrev_b32_e32 v6, 5, v15
	v_ashrrev_i16_sdwa v1, v5, sext(v1) dst_sel:DWORD dst_unused:UNUSED_PAD src0_sel:DWORD src1_sel:BYTE_0
	global_load_lds_dwordx4 v134, s[46:47]
	s_add_i32 m0, s11, 0x12000
	v_and_b32_e32 v2, 0x7fff0, v2
	v_and_b32_e32 v6, 32, v6
	v_bfe_i32 v17, v1, 0, 16
	s_add_u32 s9, s1, s14
	v_add_u32_e32 v1, v6, v17
	v_add_lshl_u32 v2, v16, v2, 13
	s_addc_u32 s13, s28, s15
	v_lshl_add_u32 v136, v1, 1, v2
	s_add_u32 s14, s46, 0x100000
	global_load_lds_dwordx4 v136, s[46:47]
	s_addc_u32 s15, s47, 0
	s_add_i32 m0, s11, 0x14000
	v_mov_b32_e32 v2, 0
	global_load_lds_dwordx4 v134, s[14:15]
	s_add_i32 m0, s11, 0x16000
	s_add_u32 s42, s9, s18
	s_addc_u32 s43, s13, s19
	s_add_i32 s57, s11, 0x2000
	global_load_lds_dwordx4 v136, s[14:15]
	s_mov_b32 m0, s11
	s_add_u32 s14, s42, 0x100000
	global_load_lds_dwordx4 v134, s[42:43]
	s_mov_b32 m0, s57
	s_addc_u32 s15, s43, 0
	s_add_i32 s60, s11, 0x4000
	global_load_lds_dwordx4 v136, s[42:43]
	s_mov_b32 m0, s60
	s_add_i32 s61, s11, 0x6000
	global_load_lds_dwordx4 v134, s[14:15]
	s_mov_b32 m0, s61
	v_mov_b32_e32 v135, v2
	global_load_lds_dwordx4 v136, s[14:15]
	v_mov_b32_e32 v137, v2
	s_cmp_eq_u32 s17, 1
	s_mov_b32 s13, 0
	v_lshl_add_u64 v[10:11], s[46:47], 0, v[134:135]
	v_lshl_add_u64 v[8:9], s[46:47], 0, v[136:137]
	v_lshl_add_u64 v[4:5], s[42:43], 0, v[134:135]
	s_cselect_b64 s[14:15], -1, 0
	s_cmp_lg_u32 s17, 1
	v_lshl_add_u64 v[6:7], s[42:43], 0, v[136:137]
	s_setprio 1
	s_cbranch_scc1 .LBB0_2472
	s_barrier
	s_setprio 0

; #define PG8_STAGE(bufoff, gbase, voff) do { _Pragma("unroll") for (int _i = 0; _i < 2; ++_i) \
;         __builtin_amdgcn_global_load_lds((const unsigned*)((const char*)(gbase) + (voff)[_i]), (PG8_LAS unsigned*)(lds + (bufoff) + ldsw + _i * 8192), 16, 0, 0); } while (0)
; #define PG8_BAR __builtin_amdgcn_s_barrier()
; template <class Epi, class Sched, bool ALIGN_EPI = false, bool SP2 = false>
; __device__ __forceinline__ void gemm_phase(PG8_LAS unsigned char* lds, const Gemm g, const Sched& S, const Epi& E) {
;     ...
;     for (int i = 0; i < 2; ++i) { int R, C; stage_rc(tid * 16 + i * 8192, R, C); const int Rb = Epi::PERM ? ((R & ~31) + perm32(R & 31)) : R;
;         voffA[i] = (unsigned)(R * K + C) * 2u; voffB[i] = (unsigned)(Rb * K + C) * 2u; }
;     const size_t kstep = (size_t)(BK * 2);
;     const size_t hstep = (size_t)HALF * K * 2;
;     const size_t tstep = 2 * hstep;
;     const unsigned ldsw = (unsigned)wid * 1024u;
;     const int aoff = lds_byte(wr * 64 + fr, fq * 8), boff = lds_byte(wc * 32 + fr, fq * 8);
;     ...
;     Unit cur, nxt; int ui = 0;
;     if (!S.next(0, cur)) return;
;     f32x4 acc[2][2][4][2];
; #pragma unroll
;     for (int a = 0; a < 2; ++a)
; #pragma unroll
;         for (int b = 0; b < 2; ++b)
; #pragma unroll
;             for (int m = 0; m < 4; ++m)
; #pragma unroll
;                 for (int n = 0; n < 2; ++n) acc[a][b][m][n] = (f32x4){0.f, 0.f, 0.f, 0.f};
;     bf16x8 At[4][2], B0[2][2], B1[2][2];
;     const char* cA = (const char*)g.A + (size_t)cur.pm * tstep + (size_t)cur.kt0 * kstep; const char* cB = (const char*)g.Bt + (size_t)cur.pn * tstep + (size_t)cur.kt0 * kstep;
;     S.a_ready(cur);
;     if constexpr (SP2) {
;         PG8_STAGE(PG8_SB(0, 0), cB, voffB); PG8_STAGE(PG8_SB(0, 1), cB + hstep, voffB); PG8_STAGE(PG8_SA(0, 0), cA, voffA); PG8_STAGE(PG8_SA(0, 1), cA + hstep, voffA);
;         if (wr == 1) PG8_BAR;
.LBB0_2641:
	s_waitcnt lgkmcnt(0)
	s_add_u32 s30, s22, 0x2100000
	s_addc_u32 s31, s23, 0
	s_andn2_b64 vcc, exec, s[6:7]
	s_cbranch_vccnz .LBB0_2793
	v_ashrrev_i32_e32 v3, 31, v1
	v_lshrrev_b32_e32 v3, 26, v3
	v_add_u32_e32 v3, v1, v3
	v_ashrrev_i32_e32 v10, 6, v3
	v_bfe_i32 v3, v1, 27, 1
	v_lshlrev_b32_e32 v2, 4, v1
	v_lshrrev_b32_e32 v3, 22, v3
	v_add_u32_e32 v3, v2, v3
	v_and_b32_e32 v3, 0xfffffc00, v3
	v_sub_u32_e32 v3, v2, v3
	v_lshrrev_b32_e32 v4, 4, v3
	v_bitop3_b32 v3, v4, v3, 32 bitop3:0x6c
	v_ashrrev_i32_e32 v5, 31, v3
	v_lshrrev_b32_e32 v5, 26, v5
	v_add_u32_e32 v5, v3, v5
	v_lshlrev_b32_e32 v4, 3, v10
	v_ashrrev_i32_e32 v11, 6, v5
	v_and_b32_e32 v5, 0xc0, v5
	v_and_b32_e32 v4, -16, v4
	v_sub_u32_e32 v3, v3, v5
	v_mov_b32_e32 v5, 1
	v_add_u32_e32 v4, v11, v4
	v_ashrrev_i16_sdwa v3, v5, sext(v3) dst_sel:DWORD dst_unused:UNUSED_PAD src0_sel:DWORD src1_sel:BYTE_0
	v_lshlrev_b32_e32 v6, 5, v10
	v_bfe_i32 v12, v3, 0, 16
	v_lshlrev_b32_e32 v3, 1, v4
	v_lshrrev_b32_e32 v7, 2, v4
	v_and_b32_e32 v8, 3, v11
	s_mov_b32 s1, 0x7ffe0
	v_and_b32_e32 v6, 32, v6
	v_and_b32_e32 v3, 24, v3
	v_and_b32_e32 v7, 4, v7
	v_and_or_b32 v8, v4, s1, v8
	v_or3_b32 v3, v8, v7, v3
	v_add_lshl_u32 v6, v6, v12, 1
	v_add_u32_e32 v2, 0x2000, v2
	v_lshl_add_u32 v186, v3, 13, v6
	v_ashrrev_i32_e32 v3, 31, v2
	v_lshrrev_b32_e32 v3, 22, v3
	v_add_u32_e32 v3, v2, v3
	v_ashrrev_i32_e32 v13, 10, v3
	v_mul_i32_i24_e32 v3, 0x400, v13
	v_sub_u32_e32 v2, v2, v3
	v_lshrrev_b32_e32 v3, 4, v2
	v_bitop3_b32 v2, v3, v2, 32 bitop3:0x6c
	v_lshl_add_u32 v184, v4, 13, v6
	v_ashrrev_i32_e32 v4, 31, v2
	v_lshrrev_b32_e32 v4, 26, v4
	v_add_u32_e32 v4, v2, v4
	v_lshlrev_b32_e32 v3, 3, v13
	v_ashrrev_i32_e32 v14, 6, v4
	v_and_b32_e32 v4, 0xc0, v4
	v_and_b32_e32 v3, -16, v3
	v_sub_u32_e32 v2, v2, v4
	s_add_u32 s57, s22, 0x14100000
	v_add_u32_e32 v3, v14, v3
	v_ashrrev_i16_sdwa v2, v5, sext(v2) dst_sel:DWORD dst_unused:UNUSED_PAD src0_sel:DWORD src1_sel:BYTE_0
	v_and_b32_e32 v5, 3, v14
	s_addc_u32 s60, s23, 0
	v_and_or_b32 v5, v3, s1, v5
	s_ashr_i32 s1, s0, 6
	s_ashr_i32 s19, s18, 31
	s_ashr_i32 s85, s84, 31
	s_ashr_i32 s16, s0, 8
	s_lshl_b32 s61, s1, 10
	s_lshl_b64 s[6:7], s[18:19], 21
	s_lshl_b64 s[8:9], s[84:85], 21
	s_add_u32 s88, s30, s8
	v_lshlrev_b32_e32 v6, 5, v13
	v_bfe_i32 v15, v2, 0, 16
	v_lshlrev_b32_e32 v2, 1, v3
	v_lshrrev_b32_e32 v4, 2, v3
	s_addc_u32 s89, s31, s9
	s_add_i32 s62, s61, 0
	v_and_b32_e32 v6, 32, v6
	v_and_b32_e32 v2, 24, v2
	v_and_b32_e32 v4, 4, v4
	s_add_i32 m0, s62, 0x10000
	v_or3_b32 v2, v5, v4, v2
	v_add_lshl_u32 v4, v6, v15, 1
	global_load_lds_dwordx4 v186, s[88:89]
	s_add_i32 m0, s62, 0x12000
	v_lshl_add_u32 v190, v2, 13, v4
	s_add_u32 s8, s88, 0x100000
	global_load_lds_dwordx4 v190, s[88:89]
	s_addc_u32 s9, s89, 0
	s_add_i32 m0, s62, 0x14000
	v_lshl_add_u32 v188, v3, 13, v4
	global_load_lds_dwordx4 v186, s[8:9]
	s_add_i32 m0, s62, 0x16000
	s_add_u32 s86, s57, s6
	s_addc_u32 s87, s60, s7
	s_add_i32 s63, s62, 0x2000
	global_load_lds_dwordx4 v190, s[8:9]
	s_mov_b32 m0, s62
	s_add_u32 s6, s86, 0x100000
	global_load_lds_dwordx4 v184, s[86:87]
	s_mov_b32 m0, s63
	s_addc_u32 s7, s87, 0
	s_add_i32 s73, s62, 0x4000
	global_load_lds_dwordx4 v188, s[86:87]
	s_mov_b32 m0, s73
	s_add_i32 s75, s62, 0x6000
	global_load_lds_dwordx4 v184, s[6:7]
	s_mov_b32 m0, s75
	v_mov_b32_e32 v193, 0
	global_load_lds_dwordx4 v188, s[6:7]
	s_load_dwordx2 s[36:37], s[34:35], 0x38
	s_load_dwordx4 s[24:27], s[34:35], 0xc0
	v_writelane_b32 v255, s96, 16
	v_mov_b32_e32 v187, v193
	v_mov_b32_e32 v191, v193
	v_mov_b32_e32 v185, v193
	v_mov_b32_e32 v189, v193
	s_cmp_eq_u32 s16, 1
	v_writelane_b32 v255, s97, 17
	s_mov_b32 s94, 0
	v_lshl_add_u64 v[8:9], s[88:89], 0, v[186:187]
	v_lshl_add_u64 v[6:7], s[88:89], 0, v[190:191]
	v_lshl_add_u64 v[4:5], s[86:87], 0, v[184:185]
	v_lshl_add_u64 v[2:3], s[86:87], 0, v[188:189]
	s_cselect_b64 s[38:39], -1, 0
	s_cmp_lg_u32 s16, 1
	s_movk_i32 s97, 0x6000
	s_setprio 1
	s_cbranch_scc1 .LBB0_2644
	s_barrier
	s_setprio 0

; #define PG8_STAGE(bufoff, gbase, voff) do { _Pragma("unroll") for (int _i = 0; _i < 2; ++_i) \
;         __builtin_amdgcn_global_load_lds((const unsigned*)((const char*)(gbase) + (voff)[_i]), (PG8_LAS unsigned*)(lds + (bufoff) + ldsw + _i * 8192), 16, 0, 0); } while (0)
; #define PG8_BAR __builtin_amdgcn_s_barrier()
; template <class Epi, class Sched, bool ALIGN_EPI = false, bool SP2 = false>
; __device__ __forceinline__ void gemm_phase(PG8_LAS unsigned char* lds, const Gemm g, const Sched& S, const Epi& E) {
;     ...
;     for (int i = 0; i < 2; ++i) { int R, C; stage_rc(tid * 16 + i * 8192, R, C); const int Rb = Epi::PERM ? ((R & ~31) + perm32(R & 31)) : R;
;         voffA[i] = (unsigned)(R * K + C) * 2u; voffB[i] = (unsigned)(Rb * K + C) * 2u; }
;     const size_t kstep = (size_t)(BK * 2);
;     const size_t hstep = (size_t)HALF * K * 2;
;     const size_t tstep = 2 * hstep;
;     const unsigned ldsw = (unsigned)wid * 1024u;
;     const int aoff = lds_byte(wr * 64 + fr, fq * 8), boff = lds_byte(wc * 32 + fr, fq * 8);
;     ...
;     Unit cur, nxt; int ui = 0;
;     if (!S.next(0, cur)) return;
;     f32x4 acc[2][2][4][2];
; #pragma unroll
;     for (int a = 0; a < 2; ++a)
; #pragma unroll
;         for (int b = 0; b < 2; ++b)
; #pragma unroll
;             for (int m = 0; m < 4; ++m)
; #pragma unroll
;                 for (int n = 0; n < 2; ++n) acc[a][b][m][n] = (f32x4){0.f, 0.f, 0.f, 0.f};
;     bf16x8 At[4][2], B0[2][2], B1[2][2];
;     const char* cA = (const char*)g.A + (size_t)cur.pm * tstep + (size_t)cur.kt0 * kstep; const char* cB = (const char*)g.Bt + (size_t)cur.pn * tstep + (size_t)cur.kt0 * kstep;
;     S.a_ready(cur);
;     if constexpr (SP2) {
;         PG8_STAGE(PG8_SB(0, 0), cB, voffB); PG8_STAGE(PG8_SB(0, 1), cB + hstep, voffB); PG8_STAGE(PG8_SA(0, 0), cA, voffA); PG8_STAGE(PG8_SA(0, 1), cA + hstep, voffA);
;         if (wr == 1) PG8_BAR;
.LBB0_3498:
	s_andn2_b64 vcc, exec, s[8:9]
	s_cbranch_vccnz .LBB0_3552
	s_waitcnt vmcnt(9)
	v_ashrrev_i32_e32 v3, 31, v1
	v_lshrrev_b32_e32 v3, 26, v3
	v_add_u32_e32 v3, v1, v3
	s_waitcnt vmcnt(4)
	v_ashrrev_i32_e32 v10, 6, v3
	v_bfe_i32 v3, v1, 27, 1
	v_lshlrev_b32_e32 v2, 4, v1
	v_lshrrev_b32_e32 v3, 22, v3
	v_add_u32_e32 v3, v2, v3
	v_and_b32_e32 v3, 0xfffffc00, v3
	v_sub_u32_e32 v3, v2, v3
	v_lshrrev_b32_e32 v4, 4, v3
	v_bitop3_b32 v3, v4, v3, 32 bitop3:0x6c
	v_ashrrev_i32_e32 v5, 31, v3
	v_lshrrev_b32_e32 v5, 26, v5
	v_add_u32_e32 v5, v3, v5
	v_lshlrev_b32_e32 v4, 3, v10
	v_ashrrev_i32_e32 v12, 6, v5
	v_and_b32_e32 v5, 0xc0, v5
	v_and_b32_e32 v4, 0xffff0, v4
	v_sub_u32_e32 v3, v3, v5
	v_mov_b32_e32 v5, 1
	s_load_dwordx4 s[8:11], s[6:7], 0xe0
	v_add_u32_e32 v4, v12, v4
	v_lshlrev_b32_e32 v6, 5, v10
	v_ashrrev_i16_sdwa v3, v5, sext(v3) dst_sel:DWORD dst_unused:UNUSED_PAD src0_sel:DWORD src1_sel:BYTE_0
	s_movk_i32 s6, 0x3000
	v_and_b32_e32 v11, 32, v6
	v_bfe_i32 v13, v3, 0, 16
	v_mul_lo_u32 v3, v4, s6
	v_or_b32_e32 v3, v3, v11
	v_add_u32_e32 v2, 0x2000, v2
	v_add_lshl_u32 v130, v3, v13, 1
	v_ashrrev_i32_e32 v3, 31, v2
	v_lshrrev_b32_e32 v3, 22, v3
	v_add_u32_e32 v3, v2, v3
	s_waitcnt lgkmcnt(0)
	s_add_u32 s46, s10, 0x2cd00000
	s_waitcnt vmcnt(2)
	v_ashrrev_i32_e32 v14, 10, v3
	s_addc_u32 s47, s11, 0
	v_mul_i32_i24_e32 v3, 0x400, v14
	s_add_u32 s48, s10, 0xe100000
	v_sub_u32_e32 v2, v2, v3
	s_addc_u32 s49, s11, 0
	v_lshrrev_b32_e32 v3, 4, v2
	s_ashr_i32 s18, s20, 6
	s_ashr_i32 s15, s14, 31
	s_ashr_i32 s7, s20, 8
	v_bitop3_b32 v2, v3, v2, 32 bitop3:0x6c
	s_lshl_b32 s50, s18, 10
	s_lshl_b64 s[16:17], s[14:15], 7
	s_mul_i32 s22, s5, 0x600000
	v_ashrrev_i32_e32 v4, 31, v2
	s_mul_hi_i32 s15, s5, 0x600000
	s_add_u32 s22, s48, s22
	v_lshrrev_b32_e32 v4, 26, v4
	s_addc_u32 s15, s49, s15
	v_add_u32_e32 v4, v2, v4
	s_add_u32 s40, s22, s16
	v_lshlrev_b32_e32 v3, 3, v14
	v_ashrrev_i32_e32 v15, 6, v4
	v_and_b32_e32 v4, 0xc0, v4
	s_addc_u32 s41, s15, s17
	s_add_i32 s51, s50, 0
	v_and_b32_e32 v3, 0xffff0, v3
	v_sub_u32_e32 v2, v2, v4
	s_add_i32 m0, s51, 0x10000
	v_add_u32_e32 v3, v15, v3
	v_lshlrev_b32_e32 v6, 5, v14
	v_ashrrev_i16_sdwa v2, v5, sext(v2) dst_sel:DWORD dst_unused:UNUSED_PAD src0_sel:DWORD src1_sel:BYTE_0
	s_mul_i32 s21, s4, 0x600000
	global_load_lds_dwordx4 v130, s[40:41]
	s_add_i32 m0, s51, 0x12000
	v_and_b32_e32 v16, 32, v6
	v_bfe_i32 v17, v2, 0, 16
	v_mul_lo_u32 v2, v3, s6
	s_mul_hi_i32 s19, s4, 0x600000
	s_add_u32 s15, s46, s21
	v_or_b32_e32 v2, v2, v16
	s_addc_u32 s19, s47, s19
	v_add_lshl_u32 v132, v2, v17, 1
	s_add_u32 s22, s40, 0x300000
	global_load_lds_dwordx4 v132, s[40:41]
	s_addc_u32 s23, s41, 0
	s_add_i32 m0, s51, 0x14000
	v_mov_b32_e32 v135, 0
	global_load_lds_dwordx4 v130, s[22:23]
	s_add_i32 m0, s51, 0x16000
	s_add_u32 s38, s15, s16
	s_addc_u32 s39, s19, s17
	s_add_i32 s52, s51, 0x2000
	global_load_lds_dwordx4 v132, s[22:23]
	s_mov_b32 m0, s51
	s_add_u32 s16, s38, 0x300000
	global_load_lds_dwordx4 v130, s[38:39]
	s_mov_b32 m0, s52
	s_addc_u32 s17, s39, 0
	s_add_i32 s53, s51, 0x4000
	global_load_lds_dwordx4 v132, s[38:39]
	s_mov_b32 m0, s53
	s_add_i32 s54, s51, 0x6000
	global_load_lds_dwordx4 v130, s[16:17]
	s_mov_b32 m0, s54
	v_mov_b32_e32 v131, v135
	global_load_lds_dwordx4 v132, s[16:17]
	v_mov_b32_e32 v133, v135
	s_cmp_eq_u32 s7, 1
	s_mov_b32 s15, 0
	v_lshl_add_u64 v[8:9], s[40:41], 0, v[130:131]
	v_lshl_add_u64 v[6:7], s[40:41], 0, v[132:133]
	v_lshl_add_u64 v[4:5], s[38:39], 0, v[130:131]
	v_lshl_add_u64 v[2:3], s[38:39], 0, v[132:133]
	s_cselect_b64 s[16:17], -1, 0
	s_cmp_lg_u32 s7, 1
	s_movk_i32 s55, 0x4000
	s_setprio 1
	s_cbranch_scc1 .LBB0_3501
	s_barrier
	s_setprio 0
